# v14: in-proj static tile order permuted so 2-tile CUs take the heavy-epilogue tiles (pn 7,8,11,12) and 3-tile CUs only plain tiles
# speedup vs baseline: 1.4928x; 1.0592x over previous
.Lgs2_done:
	s_mov_b64 exec, s[4:5]
	v_readlane_b32 s4, v255, 20
	s_mov_b32 s58, s59
	v_readlane_b32 s10, v255, 26
	v_readlane_b32 s11, v255, 27
	s_barrier
	v_readlane_b32 s5, v255, 21
	v_readlane_b32 s6, v255, 22
	s_mov_b64 s[76:77], s[10:11]
	v_mov_b32_e32 v11, v174
	s_cmpk_lt_i32 s58, 0x2a0
	s_cselect_b64 s[4:5], -1, 0
	s_cmpk_gt_i32 s58, 0x29f
	v_readfirstlane_b32 s6, v11
	v_readlane_b32 s7, v255, 23
	v_readlane_b32 s8, v255, 24
	v_readlane_b32 s9, v255, 25
	s_cbranch_scc1 .LBB0_80
	s_ashr_i32 s0, s58, 31
	s_lshr_b32 s0, s0, 29
	s_add_i32 s0, s58, s0
	s_ashr_i32 s1, s0, 3
	s_and_b32 s0, s0, -8
	s_sub_i32 s0, s58, s0
	s_cmp_lt_i32 s0, 0
	s_cselect_b32 s2, s60, 0x54
	s_mov_b32 s10, 0
	s_and_b32 s7, s0, 3
	s_cmp_eq_u32 s7, 0
	s_cbranch_scc1 .Ltpa_0
	s_cmp_eq_u32 s7, 1
	s_cbranch_scc1 .Ltpa_1
	s_cmp_eq_u32 s7, 2
	s_cbranch_scc1 .Ltpa_2
	s_sub_i32 s7, s1, 20
	s_cmp_lt_u32 s7, 8
	s_cselect_b32 s10, 0xc, s10
	s_sub_i32 s7, s1, 32
	s_cmp_lt_u32 s7, 8
	s_cselect_b32 s10, 0xfffffff4, s10
	s_sub_i32 s7, s1, 40
	s_cmp_lt_u32 s7, 4
	s_cselect_b32 s10, 0xc, s10
	s_sub_i32 s7, s1, 52
	s_cmp_lt_u32 s7, 4
	s_cselect_b32 s10, 0xfffffff4, s10
	s_sub_i32 s7, s1, 56
	s_cmp_lt_u32 s7, 4
	s_cselect_b32 s10, 0x8, s10
	s_sub_i32 s7, s1, 64
	s_cmp_lt_u32 s7, 4
	s_cselect_b32 s10, 0xfffffff8, s10
	s_sub_i32 s7, s1, 68
	s_cmp_lt_u32 s7, 8
	s_cselect_b32 s10, 0xffffff4c, s10
	s_branch .Ltpa_done
.Ltpa_0:
	s_sub_i32 s7, s1, 20
	s_cmp_lt_u32 s7, 8
	s_cselect_b32 s10, 0x2c, s10
	s_sub_i32 s7, s1, 28
	s_cmp_lt_u32 s7, 4
	s_cselect_b32 s10, 0xb4, s10
	s_sub_i32 s7, s1, 52
	s_cmp_lt_u32 s7, 4
	s_cselect_b32 s10, 0xa0, s10
	s_sub_i32 s7, s1, 64
	s_cmp_lt_u32 s7, 8
	s_cselect_b32 s10, 0xffffffd4, s10
	s_branch .Ltpa_done
.Ltpa_1:
	s_sub_i32 s7, s1, 4
	s_cmp_lt_u32 s7, 12
	s_cselect_b32 s10, 0x10, s10
	s_sub_i32 s7, s1, 16
	s_cmp_lt_u32 s7, 4
	s_cselect_b32 s10, 0x24, s10
	s_sub_i32 s7, s1, 20
	s_cmp_lt_u32 s7, 12
	s_cselect_b32 s10, 0xfffffff0, s10
	s_sub_i32 s7, s1, 52
	s_cmp_lt_u32 s7, 4
	s_cselect_b32 s10, 0xffffffdc, s10
	s_sub_i32 s7, s1, 56
	s_cmp_lt_u32 s7, 8
	s_cselect_b32 s10, 0xb4, s10
	s_branch .Ltpa_done
.Ltpa_2:
	s_sub_i32 s7, s1, 0
	s_cmp_lt_u32 s7, 12
	s_cselect_b32 s10, 0x14, s10
	s_sub_i32 s7, s1, 12
	s_cmp_lt_u32 s7, 4
	s_cselect_b32 s10, 0x28, s10
	s_sub_i32 s7, s1, 20
	s_cmp_lt_u32 s7, 12
	s_cselect_b32 s10, 0xffffffec, s10
	s_sub_i32 s7, s1, 32
	s_cmp_lt_u32 s7, 8
	s_cselect_b32 s10, 0x18, s10
	s_sub_i32 s7, s1, 40
	s_cmp_lt_u32 s7, 4
	s_cselect_b32 s10, 0xffffff4c, s10
	s_sub_i32 s7, s1, 44
	s_cmp_lt_u32 s7, 4
	s_cselect_b32 s10, 0xffffff60, s10
	s_sub_i32 s7, s1, 52
	s_cmp_lt_u32 s7, 4
	s_cselect_b32 s10, 0xffffffd8, s10
	s_sub_i32 s7, s1, 56
	s_cmp_lt_u32 s7, 8
	s_cselect_b32 s10, 0xffffffe8, s10
.Ltpa_done:
	s_add_i32 s1, s1, s10
	s_mul_i32 s0, s0, s2
	s_add_i32 s0, s0, s1
	s_mul_hi_i32 s1, s0, 0x92492493
	s_add_i32 s1, s1, s0
	s_lshr_b32 s2, s1, 31
	s_ashr_i32 s1, s1, 6
	s_add_i32 s1, s1, s2
	s_lshl_b32 s2, s1, 3
	s_mulk_i32 s1, 0x70
	s_sub_i32 s0, s0, s1
	s_bfe_i32 s1, s0, 0x80000
	s_bfe_u32 s1, s1, 0x3000c
	s_add_i32 s1, s0, s1
	s_bfe_i32 s7, s1, 0x80000
	s_and_b32 s1, s1, 0xf8
	s_sub_i32 s0, s0, s1
	s_sext_i32_i16 s7, s7
	s_sext_i32_i8 s0, s0
	s_add_i32 s10, s2, s0
	s_ashr_i32 s92, s7, 3

.LBB0_86:
	s_add_i32 s47, s47, 1
	s_mul_i32 s8, s47, s33
	s_mul_hi_u32 s9, s47, s3
	s_add_i32 s9, s9, s8
	s_mul_i32 s8, s47, s3
	s_add_u32 s22, s8, s58
	s_addc_u32 s23, s9, s48
	v_mov_b64_e32 v[2:3], 0x2a0
	v_cmp_lt_i64_e64 s[8:9], s[22:23], v[2:3]
	v_mov_b64_e32 v[2:3], 0x29f
	v_cmp_gt_i64_e32 vcc, s[22:23], v[2:3]
	s_cbranch_vccnz .LBB0_88
	s_ashr_i32 s11, s22, 31
	s_lshr_b32 s11, s11, 29
	s_add_i32 s11, s22, s11
	s_ashr_i32 s20, s11, 3
	s_and_b32 s11, s11, -8
	s_sub_i32 s11, s22, s11
	s_cmp_lt_i32 s11, 0
	s_cselect_b32 s21, s60, 0x54
	s_mov_b32 s23, 0
	s_and_b32 s22, s11, 3
	s_cmp_eq_u32 s22, 0
	s_cbranch_scc1 .Ltpb_0
	s_cmp_eq_u32 s22, 1
	s_cbranch_scc1 .Ltpb_1
	s_cmp_eq_u32 s22, 2
	s_cbranch_scc1 .Ltpb_2
	s_sub_i32 s22, s20, 20
	s_cmp_lt_u32 s22, 8
	s_cselect_b32 s23, 0xc, s23
	s_sub_i32 s22, s20, 32
	s_cmp_lt_u32 s22, 8
	s_cselect_b32 s23, 0xfffffff4, s23
	s_sub_i32 s22, s20, 40
	s_cmp_lt_u32 s22, 4
	s_cselect_b32 s23, 0xc, s23
	s_sub_i32 s22, s20, 52
	s_cmp_lt_u32 s22, 4
	s_cselect_b32 s23, 0xfffffff4, s23
	s_sub_i32 s22, s20, 56
	s_cmp_lt_u32 s22, 4
	s_cselect_b32 s23, 0x8, s23
	s_sub_i32 s22, s20, 64
	s_cmp_lt_u32 s22, 4
	s_cselect_b32 s23, 0xfffffff8, s23
	s_sub_i32 s22, s20, 68
	s_cmp_lt_u32 s22, 8
	s_cselect_b32 s23, 0xffffff4c, s23
	s_branch .Ltpb_done
.Ltpb_0:
	s_sub_i32 s22, s20, 20
	s_cmp_lt_u32 s22, 8
	s_cselect_b32 s23, 0x2c, s23
	s_sub_i32 s22, s20, 28
	s_cmp_lt_u32 s22, 4
	s_cselect_b32 s23, 0xb4, s23
	s_sub_i32 s22, s20, 52
	s_cmp_lt_u32 s22, 4
	s_cselect_b32 s23, 0xa0, s23
	s_sub_i32 s22, s20, 64
	s_cmp_lt_u32 s22, 8
	s_cselect_b32 s23, 0xffffffd4, s23
	s_branch .Ltpb_done
.Ltpb_1:
	s_sub_i32 s22, s20, 4
	s_cmp_lt_u32 s22, 12
	s_cselect_b32 s23, 0x10, s23
	s_sub_i32 s22, s20, 16
	s_cmp_lt_u32 s22, 4
	s_cselect_b32 s23, 0x24, s23
	s_sub_i32 s22, s20, 20
	s_cmp_lt_u32 s22, 12
	s_cselect_b32 s23, 0xfffffff0, s23
	s_sub_i32 s22, s20, 52
	s_cmp_lt_u32 s22, 4
	s_cselect_b32 s23, 0xffffffdc, s23
	s_sub_i32 s22, s20, 56
	s_cmp_lt_u32 s22, 8
	s_cselect_b32 s23, 0xb4, s23
	s_branch .Ltpb_done
.Ltpb_2:
	s_sub_i32 s22, s20, 0
	s_cmp_lt_u32 s22, 12
	s_cselect_b32 s23, 0x14, s23
	s_sub_i32 s22, s20, 12
	s_cmp_lt_u32 s22, 4
	s_cselect_b32 s23, 0x28, s23
	s_sub_i32 s22, s20, 20
	s_cmp_lt_u32 s22, 12
	s_cselect_b32 s23, 0xffffffec, s23
	s_sub_i32 s22, s20, 32
	s_cmp_lt_u32 s22, 8
	s_cselect_b32 s23, 0x18, s23
	s_sub_i32 s22, s20, 40
	s_cmp_lt_u32 s22, 4
	s_cselect_b32 s23, 0xffffff4c, s23
	s_sub_i32 s22, s20, 44
	s_cmp_lt_u32 s22, 4
	s_cselect_b32 s23, 0xffffff60, s23
	s_sub_i32 s22, s20, 52
	s_cmp_lt_u32 s22, 4
	s_cselect_b32 s23, 0xffffffd8, s23
	s_sub_i32 s22, s20, 56
	s_cmp_lt_u32 s22, 8
	s_cselect_b32 s23, 0xffffffe8, s23
.Ltpb_done:
	s_add_i32 s20, s20, s23
	s_mul_i32 s11, s11, s21
	s_add_i32 s11, s11, s20
	s_mul_hi_i32 s20, s11, 0x92492493
	s_add_i32 s20, s20, s11
	s_lshr_b32 s21, s20, 31
	s_ashr_i32 s20, s20, 6
	s_add_i32 s20, s20, s21
	s_lshl_b32 s21, s20, 3
	s_sub_i32 s22, 48, s21
	s_min_i32 s22, s22, 8
	s_abs_i32 s23, s22
	v_cvt_f32_u32_e32 v0, s23
	s_sub_i32 s41, 0, s23
	s_mulk_i32 s20, 0x70
	s_sub_i32 s11, s11, s20
	v_rcp_iflag_f32_e32 v0, v0
	s_abs_i32 s20, s11
	s_xor_b32 s30, s11, s22
	s_ashr_i32 s30, s30, 31
	v_mul_f32_e32 v0, 0x4f7ffffe, v0
	v_cvt_u32_f32_e32 v0, v0
	s_nop 0
	v_readfirstlane_b32 s44, v0
	s_mul_i32 s41, s41, s44
	s_mul_hi_u32 s41, s44, s41
	s_add_i32 s44, s44, s41
	s_mul_hi_u32 s41, s20, s44
	s_mul_i32 s44, s41, s23
	s_sub_i32 s20, s20, s44
	s_add_i32 s45, s41, 1
	s_sub_i32 s44, s20, s23
	s_cmp_ge_u32 s20, s23
	s_cselect_b32 s41, s45, s41
	s_cselect_b32 s20, s44, s20
	s_add_i32 s44, s41, 1
	s_cmp_ge_u32 s20, s23
	s_cselect_b32 s20, s44, s41
	s_xor_b32 s20, s20, s30
	s_sub_i32 s84, s20, s30
	s_mul_i32 s20, s84, s22
	s_sub_i32 s11, s11, s20
	s_add_i32 s86, s21, s11
